# run-scan phase: all 32 (or 8) steps' loads of a task issued up front, serial scan consumes them with counted vmcnt waits (was 8 loads / wait / 8 steps, four times); on top of the barrier poll change
# speedup vs baseline: 1.0190x; 1.0038x over previous
; DI void phase_rscan(int g, bf16* RT, const float* RDEC, int bid, int nb, int tid) {
;     const int rps = g < 2 ? 32 : 8, combos = g < 2 ? 8 : 32, ntasks = combos * 8192;
;     for (int task = bid * NT + tid; task < ntasks; task += nb * NT) {
;         const int e = task & 8191, combo = task >> 13;
;         const int k = (((e >> 8) & 3) << 5) + (((e >> 6) & 3) << 3) + ((2 * e) & 7);
;         bf16* sp = RT + (size_t)(combo * rps) * 16384 + 2 * e;
;         const float* ap = RDEC + (size_t)(combo * rps) * 256 + 2 * k;
;         float S0 = 0.f, S1 = 0.f;
;         for (int st0 = 0; st0 < rps; st0 += 8) {
;             unsigned u[8]; float4 a[8];
; #pragma unroll
;             for (int j = 0; j < 8; ++j) { u[j] = *(const unsigned*)(sp + (size_t)j * 16384); a[j] = *(const float4*)(ap + (size_t)j * 256); }
.LBB0_338:
	v_lshlrev_b32_e32 v5, 1, v1
	v_lshrrev_b32_e32 v3, 3, v1
	v_and_b32_e32 v5, 6, v5
	s_movk_i32 s1, 0x78
	v_ashrrev_i32_e32 v2, 13, v1
	v_and_or_b32 v5, v3, s1, v5
	v_readlane_b32 s1, v254, 44
	v_readlane_b32 s2, v252, 28
	v_readlane_b32 s3, v252, 29
	v_lshlrev_b32_e32 v6, s1, v2
	v_ashrrev_i32_e32 v7, 31, v6
	v_lshlrev_b64 v[2:3], 15, v[6:7]
	v_lshlrev_b32_e32 v8, 2, v1
	v_lshl_add_u64 v[2:3], s[2:3], 0, v[2:3]
	v_and_b32_e32 v8, 0x7ffc, v8
	v_mov_b32_e32 v9, v0
	v_lshlrev_b64 v[6:7], 10, v[6:7]
	v_lshl_add_u64 v[2:3], v[2:3], 0, v[8:9]
	v_lshl_add_u64 v[6:7], s[26:27], 0, v[6:7]
	v_lshlrev_b32_e32 v8, 3, v5
	v_lshl_add_u64 v[6:7], v[6:7], 0, v[8:9]
	v_mov_b32_e32 v8, 0
	s_mov_b32 s1, 0
	v_mov_b32_e32 v9, v8
	s_mov_b64 s[2:3], 0x8000
	s_mov_b64 vcc, 0x1000
	v_mov_b32_e32 v10, v2
	v_mov_b32_e32 v11, v3
	v_mov_b32_e32 v12, v6
	v_mov_b32_e32 v13, v7
	s_cmp_lg_u64 s[88:89], 0
	s_cbranch_scc0 .Lrs_one
	global_load_dword v54, v[10:11], off
	global_load_dwordx2 v[86:87], v[12:13], off
	v_lshl_add_u64 v[10:11], v[10:11], 0, s[2:3]
	global_load_dword v55, v[10:11], off
	global_load_dwordx2 v[88:89], v[12:13], off offset:1024
	v_lshl_add_u64 v[10:11], v[10:11], 0, s[2:3]
	global_load_dword v56, v[10:11], off
	global_load_dwordx2 v[90:91], v[12:13], off offset:2048
	v_lshl_add_u64 v[10:11], v[10:11], 0, s[2:3]
	global_load_dword v57, v[10:11], off
	global_load_dwordx2 v[92:93], v[12:13], off offset:3072
	v_lshl_add_u64 v[10:11], v[10:11], 0, s[2:3]
	v_lshl_add_u64 v[12:13], v[12:13], 0, vcc
	global_load_dword v58, v[10:11], off
	global_load_dwordx2 v[94:95], v[12:13], off
	v_lshl_add_u64 v[10:11], v[10:11], 0, s[2:3]
	global_load_dword v59, v[10:11], off
	global_load_dwordx2 v[96:97], v[12:13], off offset:1024
	v_lshl_add_u64 v[10:11], v[10:11], 0, s[2:3]
	global_load_dword v60, v[10:11], off
	global_load_dwordx2 v[98:99], v[12:13], off offset:2048
	v_lshl_add_u64 v[10:11], v[10:11], 0, s[2:3]
	global_load_dword v61, v[10:11], off
	global_load_dwordx2 v[100:101], v[12:13], off offset:3072
	v_lshl_add_u64 v[10:11], v[10:11], 0, s[2:3]
	v_lshl_add_u64 v[12:13], v[12:13], 0, vcc
	global_load_dword v62, v[10:11], off
	global_load_dwordx2 v[102:103], v[12:13], off
	v_lshl_add_u64 v[10:11], v[10:11], 0, s[2:3]
	global_load_dword v63, v[10:11], off
	global_load_dwordx2 v[104:105], v[12:13], off offset:1024
	v_lshl_add_u64 v[10:11], v[10:11], 0, s[2:3]
	global_load_dword v64, v[10:11], off
	global_load_dwordx2 v[106:107], v[12:13], off offset:2048
	v_lshl_add_u64 v[10:11], v[10:11], 0, s[2:3]
	global_load_dword v65, v[10:11], off
	global_load_dwordx2 v[108:109], v[12:13], off offset:3072
	v_lshl_add_u64 v[10:11], v[10:11], 0, s[2:3]
	v_lshl_add_u64 v[12:13], v[12:13], 0, vcc
	global_load_dword v66, v[10:11], off
	global_load_dwordx2 v[110:111], v[12:13], off
	v_lshl_add_u64 v[10:11], v[10:11], 0, s[2:3]
	global_load_dword v67, v[10:11], off
	global_load_dwordx2 v[112:113], v[12:13], off offset:1024
	v_lshl_add_u64 v[10:11], v[10:11], 0, s[2:3]
	global_load_dword v68, v[10:11], off
	global_load_dwordx2 v[114:115], v[12:13], off offset:2048
	v_lshl_add_u64 v[10:11], v[10:11], 0, s[2:3]
	global_load_dword v69, v[10:11], off
	global_load_dwordx2 v[116:117], v[12:13], off offset:3072
	v_lshl_add_u64 v[10:11], v[10:11], 0, s[2:3]
	v_lshl_add_u64 v[12:13], v[12:13], 0, vcc
	global_load_dword v70, v[10:11], off
	global_load_dwordx2 v[118:119], v[12:13], off
	v_lshl_add_u64 v[10:11], v[10:11], 0, s[2:3]
	global_load_dword v71, v[10:11], off
	global_load_dwordx2 v[120:121], v[12:13], off offset:1024
	v_lshl_add_u64 v[10:11], v[10:11], 0, s[2:3]
	global_load_dword v72, v[10:11], off
	global_load_dwordx2 v[122:123], v[12:13], off offset:2048
	v_lshl_add_u64 v[10:11], v[10:11], 0, s[2:3]
	global_load_dword v73, v[10:11], off
	global_load_dwordx2 v[124:125], v[12:13], off offset:3072
	v_lshl_add_u64 v[10:11], v[10:11], 0, s[2:3]
	v_lshl_add_u64 v[12:13], v[12:13], 0, vcc
	global_load_dword v74, v[10:11], off
	global_load_dwordx2 v[126:127], v[12:13], off
	v_lshl_add_u64 v[10:11], v[10:11], 0, s[2:3]
	global_load_dword v75, v[10:11], off
	global_load_dwordx2 v[128:129], v[12:13], off offset:1024
	v_lshl_add_u64 v[10:11], v[10:11], 0, s[2:3]
	global_load_dword v76, v[10:11], off
	global_load_dwordx2 v[130:131], v[12:13], off offset:2048
	v_lshl_add_u64 v[10:11], v[10:11], 0, s[2:3]
	global_load_dword v77, v[10:11], off
	global_load_dwordx2 v[132:133], v[12:13], off offset:3072
	v_lshl_add_u64 v[10:11], v[10:11], 0, s[2:3]
	v_lshl_add_u64 v[12:13], v[12:13], 0, vcc
	global_load_dword v78, v[10:11], off
	global_load_dwordx2 v[134:135], v[12:13], off
	v_lshl_add_u64 v[10:11], v[10:11], 0, s[2:3]
	global_load_dword v79, v[10:11], off
	global_load_dwordx2 v[136:137], v[12:13], off offset:1024
	v_lshl_add_u64 v[10:11], v[10:11], 0, s[2:3]
	global_load_dword v80, v[10:11], off
	global_load_dwordx2 v[138:139], v[12:13], off offset:2048
	v_lshl_add_u64 v[10:11], v[10:11], 0, s[2:3]
	global_load_dword v81, v[10:11], off
	global_load_dwordx2 v[140:141], v[12:13], off offset:3072
	v_lshl_add_u64 v[10:11], v[10:11], 0, s[2:3]
	v_lshl_add_u64 v[12:13], v[12:13], 0, vcc
	global_load_dword v82, v[10:11], off
	global_load_dwordx2 v[142:143], v[12:13], off
	v_lshl_add_u64 v[10:11], v[10:11], 0, s[2:3]
	global_load_dword v83, v[10:11], off
	global_load_dwordx2 v[144:145], v[12:13], off offset:1024
	v_lshl_add_u64 v[10:11], v[10:11], 0, s[2:3]
	global_load_dword v84, v[10:11], off
	global_load_dwordx2 v[146:147], v[12:13], off offset:2048
	v_lshl_add_u64 v[10:11], v[10:11], 0, s[2:3]
	global_load_dword v85, v[10:11], off
	global_load_dwordx2 v[150:151], v[12:13], off offset:3072
	v_cvt_pk_bf16_f32 v5, v8, v9
	global_store_dword v[2:3], v5, off
	s_waitcnt vmcnt(63)
; DI float bflo(unsigned w) { return __uint_as_float(w << 16); }
; DI float bfhi(unsigned w) { return __uint_as_float(w & 0xffff0000u); }
; DI unsigned pk(float lo, float hi) { return pg8::cvt_pk_bf16(lo, hi); }
; DI void phase_rscan(int g, bf16* RT, const float* RDEC, int bid, int nb, int tid) {
;     ...
; #pragma unroll
;             for (int j = 0; j < 8; ++j) { *(unsigned*)(sp + (size_t)j * 16384) = pk(S0, S1); S0 = a[j].x * S0 + bflo(u[j]); S1 = a[j].y * S1 + bfhi(u[j]); }
	v_lshlrev_b32_e32 v40, 16, v54
	v_and_b32_e32 v41, 0xffff0000, v54
	v_lshl_add_u64 v[2:3], v[2:3], 0, s[2:3]
	v_pk_fma_f32 v[8:9], v[8:9], v[86:87], v[40:41]
	s_nop 0
	v_cvt_pk_bf16_f32 v5, v8, v9
	global_store_dword v[2:3], v5, off
	s_waitcnt vmcnt(62)
	v_lshlrev_b32_e32 v40, 16, v55
	v_and_b32_e32 v41, 0xffff0000, v55
	v_lshl_add_u64 v[2:3], v[2:3], 0, s[2:3]
	v_pk_fma_f32 v[8:9], v[8:9], v[88:89], v[40:41]
	s_nop 0
	v_cvt_pk_bf16_f32 v5, v8, v9
	global_store_dword v[2:3], v5, off
	s_waitcnt vmcnt(61)
	v_lshlrev_b32_e32 v40, 16, v56
	v_and_b32_e32 v41, 0xffff0000, v56
	v_lshl_add_u64 v[2:3], v[2:3], 0, s[2:3]
	v_pk_fma_f32 v[8:9], v[8:9], v[90:91], v[40:41]
	s_nop 0
	v_cvt_pk_bf16_f32 v5, v8, v9
	global_store_dword v[2:3], v5, off
	s_waitcnt vmcnt(60)
	v_lshlrev_b32_e32 v40, 16, v57
	v_and_b32_e32 v41, 0xffff0000, v57
	v_lshl_add_u64 v[2:3], v[2:3], 0, s[2:3]
	v_pk_fma_f32 v[8:9], v[8:9], v[92:93], v[40:41]
	s_nop 0
	v_cvt_pk_bf16_f32 v5, v8, v9
	global_store_dword v[2:3], v5, off
	s_waitcnt vmcnt(59)
	v_lshlrev_b32_e32 v40, 16, v58
	v_and_b32_e32 v41, 0xffff0000, v58
	v_lshl_add_u64 v[2:3], v[2:3], 0, s[2:3]
	v_pk_fma_f32 v[8:9], v[8:9], v[94:95], v[40:41]
	s_nop 0
	v_cvt_pk_bf16_f32 v5, v8, v9
	global_store_dword v[2:3], v5, off
	s_waitcnt vmcnt(58)
	v_lshlrev_b32_e32 v40, 16, v59
	v_and_b32_e32 v41, 0xffff0000, v59
	v_lshl_add_u64 v[2:3], v[2:3], 0, s[2:3]
	v_pk_fma_f32 v[8:9], v[8:9], v[96:97], v[40:41]
	s_nop 0
	v_cvt_pk_bf16_f32 v5, v8, v9
	global_store_dword v[2:3], v5, off
	s_waitcnt vmcnt(57)
	v_lshlrev_b32_e32 v40, 16, v60
	v_and_b32_e32 v41, 0xffff0000, v60
	v_lshl_add_u64 v[2:3], v[2:3], 0, s[2:3]
	v_pk_fma_f32 v[8:9], v[8:9], v[98:99], v[40:41]
	s_nop 0
	v_cvt_pk_bf16_f32 v5, v8, v9
	global_store_dword v[2:3], v5, off
	s_waitcnt vmcnt(56)
	v_lshlrev_b32_e32 v40, 16, v61
	v_and_b32_e32 v41, 0xffff0000, v61
	v_lshl_add_u64 v[2:3], v[2:3], 0, s[2:3]
	v_pk_fma_f32 v[8:9], v[8:9], v[100:101], v[40:41]
	s_nop 0
	v_cvt_pk_bf16_f32 v5, v8, v9
	global_store_dword v[2:3], v5, off
	s_waitcnt vmcnt(55)
	v_lshlrev_b32_e32 v40, 16, v62
	v_and_b32_e32 v41, 0xffff0000, v62
	v_lshl_add_u64 v[2:3], v[2:3], 0, s[2:3]
	v_pk_fma_f32 v[8:9], v[8:9], v[102:103], v[40:41]
	s_nop 0
	v_cvt_pk_bf16_f32 v5, v8, v9
	global_store_dword v[2:3], v5, off
	s_waitcnt vmcnt(54)
	v_lshlrev_b32_e32 v40, 16, v63
	v_and_b32_e32 v41, 0xffff0000, v63
	v_lshl_add_u64 v[2:3], v[2:3], 0, s[2:3]
	v_pk_fma_f32 v[8:9], v[8:9], v[104:105], v[40:41]
	s_nop 0
	v_cvt_pk_bf16_f32 v5, v8, v9
	global_store_dword v[2:3], v5, off
	s_waitcnt vmcnt(53)
	v_lshlrev_b32_e32 v40, 16, v64
	v_and_b32_e32 v41, 0xffff0000, v64
	v_lshl_add_u64 v[2:3], v[2:3], 0, s[2:3]
	v_pk_fma_f32 v[8:9], v[8:9], v[106:107], v[40:41]
	s_nop 0
	v_cvt_pk_bf16_f32 v5, v8, v9
	global_store_dword v[2:3], v5, off
	s_waitcnt vmcnt(52)
	v_lshlrev_b32_e32 v40, 16, v65
	v_and_b32_e32 v41, 0xffff0000, v65
	v_lshl_add_u64 v[2:3], v[2:3], 0, s[2:3]
	v_pk_fma_f32 v[8:9], v[8:9], v[108:109], v[40:41]
	s_nop 0
	v_cvt_pk_bf16_f32 v5, v8, v9
	global_store_dword v[2:3], v5, off
	s_waitcnt vmcnt(51)
	v_lshlrev_b32_e32 v40, 16, v66
	v_and_b32_e32 v41, 0xffff0000, v66
	v_lshl_add_u64 v[2:3], v[2:3], 0, s[2:3]
	v_pk_fma_f32 v[8:9], v[8:9], v[110:111], v[40:41]
	s_nop 0
	v_cvt_pk_bf16_f32 v5, v8, v9
	global_store_dword v[2:3], v5, off
	s_waitcnt vmcnt(50)
	v_lshlrev_b32_e32 v40, 16, v67
	v_and_b32_e32 v41, 0xffff0000, v67
	v_lshl_add_u64 v[2:3], v[2:3], 0, s[2:3]
	v_pk_fma_f32 v[8:9], v[8:9], v[112:113], v[40:41]
	s_nop 0
	v_cvt_pk_bf16_f32 v5, v8, v9
	global_store_dword v[2:3], v5, off
	s_waitcnt vmcnt(49)
	v_lshlrev_b32_e32 v40, 16, v68
	v_and_b32_e32 v41, 0xffff0000, v68
	v_lshl_add_u64 v[2:3], v[2:3], 0, s[2:3]
	v_pk_fma_f32 v[8:9], v[8:9], v[114:115], v[40:41]
	s_nop 0
	v_cvt_pk_bf16_f32 v5, v8, v9
	global_store_dword v[2:3], v5, off
	s_waitcnt vmcnt(48)
	v_lshlrev_b32_e32 v40, 16, v69
	v_and_b32_e32 v41, 0xffff0000, v69
	v_lshl_add_u64 v[2:3], v[2:3], 0, s[2:3]
	v_pk_fma_f32 v[8:9], v[8:9], v[116:117], v[40:41]
	s_nop 0
	v_cvt_pk_bf16_f32 v5, v8, v9
	global_store_dword v[2:3], v5, off
	s_waitcnt vmcnt(47)
	v_lshlrev_b32_e32 v40, 16, v70
	v_and_b32_e32 v41, 0xffff0000, v70
	v_lshl_add_u64 v[2:3], v[2:3], 0, s[2:3]
	v_pk_fma_f32 v[8:9], v[8:9], v[118:119], v[40:41]
	s_nop 0
	v_cvt_pk_bf16_f32 v5, v8, v9
	global_store_dword v[2:3], v5, off
	s_waitcnt vmcnt(46)
	v_lshlrev_b32_e32 v40, 16, v71
	v_and_b32_e32 v41, 0xffff0000, v71
	v_lshl_add_u64 v[2:3], v[2:3], 0, s[2:3]
	v_pk_fma_f32 v[8:9], v[8:9], v[120:121], v[40:41]
	s_nop 0
	v_cvt_pk_bf16_f32 v5, v8, v9
	global_store_dword v[2:3], v5, off
	s_waitcnt vmcnt(45)
	v_lshlrev_b32_e32 v40, 16, v72
	v_and_b32_e32 v41, 0xffff0000, v72
	v_lshl_add_u64 v[2:3], v[2:3], 0, s[2:3]
	v_pk_fma_f32 v[8:9], v[8:9], v[122:123], v[40:41]
	s_nop 0
	v_cvt_pk_bf16_f32 v5, v8, v9
	global_store_dword v[2:3], v5, off
	s_waitcnt vmcnt(44)
	v_lshlrev_b32_e32 v40, 16, v73
	v_and_b32_e32 v41, 0xffff0000, v73
	v_lshl_add_u64 v[2:3], v[2:3], 0, s[2:3]
	v_pk_fma_f32 v[8:9], v[8:9], v[124:125], v[40:41]
	s_nop 0
	v_cvt_pk_bf16_f32 v5, v8, v9
	global_store_dword v[2:3], v5, off
	s_waitcnt vmcnt(43)
	v_lshlrev_b32_e32 v40, 16, v74
	v_and_b32_e32 v41, 0xffff0000, v74
	v_lshl_add_u64 v[2:3], v[2:3], 0, s[2:3]
	v_pk_fma_f32 v[8:9], v[8:9], v[126:127], v[40:41]
	s_nop 0
	v_cvt_pk_bf16_f32 v5, v8, v9
	global_store_dword v[2:3], v5, off
	s_waitcnt vmcnt(42)
	v_lshlrev_b32_e32 v40, 16, v75
	v_and_b32_e32 v41, 0xffff0000, v75
	v_lshl_add_u64 v[2:3], v[2:3], 0, s[2:3]
	v_pk_fma_f32 v[8:9], v[8:9], v[128:129], v[40:41]
	s_nop 0
	v_cvt_pk_bf16_f32 v5, v8, v9
	global_store_dword v[2:3], v5, off
	s_waitcnt vmcnt(41)
; DI float bflo(unsigned w) { return __uint_as_float(w << 16); }
; DI float bfhi(unsigned w) { return __uint_as_float(w & 0xffff0000u); }
; DI unsigned pk(float lo, float hi) { return pg8::cvt_pk_bf16(lo, hi); }
; DI void phase_rscan(int g, bf16* RT, const float* RDEC, int bid, int nb, int tid) {
;     ...
;         for (int st0 = 0; st0 < rps; st0 += 8) {
;             unsigned u[8]; float4 a[8];
; #pragma unroll
;             for (int j = 0; j < 8; ++j) { u[j] = *(const unsigned*)(sp + (size_t)j * 16384); a[j] = *(const float4*)(ap + (size_t)j * 256); }
; #pragma unroll
;             for (int j = 0; j < 8; ++j) { *(unsigned*)(sp + (size_t)j * 16384) = pk(S0, S1); S0 = a[j].x * S0 + bflo(u[j]); S1 = a[j].y * S1 + bfhi(u[j]); }
;             sp += 8 * 16384; ap += 8 * 256;
;         }
;     }
	v_lshlrev_b32_e32 v40, 16, v76
	v_and_b32_e32 v41, 0xffff0000, v76
	v_lshl_add_u64 v[2:3], v[2:3], 0, s[2:3]
	v_pk_fma_f32 v[8:9], v[8:9], v[130:131], v[40:41]
	s_nop 0
	v_cvt_pk_bf16_f32 v5, v8, v9
	global_store_dword v[2:3], v5, off
	s_waitcnt vmcnt(40)
	v_lshlrev_b32_e32 v40, 16, v77
	v_and_b32_e32 v41, 0xffff0000, v77
	v_lshl_add_u64 v[2:3], v[2:3], 0, s[2:3]
	v_pk_fma_f32 v[8:9], v[8:9], v[132:133], v[40:41]
	s_nop 0
	v_cvt_pk_bf16_f32 v5, v8, v9
	global_store_dword v[2:3], v5, off
	s_waitcnt vmcnt(39)
	v_lshlrev_b32_e32 v40, 16, v78
	v_and_b32_e32 v41, 0xffff0000, v78
	v_lshl_add_u64 v[2:3], v[2:3], 0, s[2:3]
	v_pk_fma_f32 v[8:9], v[8:9], v[134:135], v[40:41]
	s_nop 0
	v_cvt_pk_bf16_f32 v5, v8, v9
	global_store_dword v[2:3], v5, off
	s_waitcnt vmcnt(38)
	v_lshlrev_b32_e32 v40, 16, v79
	v_and_b32_e32 v41, 0xffff0000, v79
	v_lshl_add_u64 v[2:3], v[2:3], 0, s[2:3]
	v_pk_fma_f32 v[8:9], v[8:9], v[136:137], v[40:41]
	s_nop 0
	v_cvt_pk_bf16_f32 v5, v8, v9
	global_store_dword v[2:3], v5, off
	s_waitcnt vmcnt(37)
	v_lshlrev_b32_e32 v40, 16, v80
	v_and_b32_e32 v41, 0xffff0000, v80
	v_lshl_add_u64 v[2:3], v[2:3], 0, s[2:3]
	v_pk_fma_f32 v[8:9], v[8:9], v[138:139], v[40:41]
	s_nop 0
	v_cvt_pk_bf16_f32 v5, v8, v9
	global_store_dword v[2:3], v5, off
	s_waitcnt vmcnt(36)
	v_lshlrev_b32_e32 v40, 16, v81
	v_and_b32_e32 v41, 0xffff0000, v81
	v_lshl_add_u64 v[2:3], v[2:3], 0, s[2:3]
	v_pk_fma_f32 v[8:9], v[8:9], v[140:141], v[40:41]
	s_nop 0
	v_cvt_pk_bf16_f32 v5, v8, v9
	global_store_dword v[2:3], v5, off
	s_waitcnt vmcnt(35)
	v_lshlrev_b32_e32 v40, 16, v82
	v_and_b32_e32 v41, 0xffff0000, v82
	v_lshl_add_u64 v[2:3], v[2:3], 0, s[2:3]
	v_pk_fma_f32 v[8:9], v[8:9], v[142:143], v[40:41]
	s_nop 0
	v_cvt_pk_bf16_f32 v5, v8, v9
	global_store_dword v[2:3], v5, off
	s_waitcnt vmcnt(34)
	v_lshlrev_b32_e32 v40, 16, v83
	v_and_b32_e32 v41, 0xffff0000, v83
	v_lshl_add_u64 v[2:3], v[2:3], 0, s[2:3]
	v_pk_fma_f32 v[8:9], v[8:9], v[144:145], v[40:41]
	s_nop 0
	v_cvt_pk_bf16_f32 v5, v8, v9
	global_store_dword v[2:3], v5, off
	s_waitcnt vmcnt(33)
	v_lshlrev_b32_e32 v40, 16, v84
	v_and_b32_e32 v41, 0xffff0000, v84
	v_lshl_add_u64 v[2:3], v[2:3], 0, s[2:3]
	v_pk_fma_f32 v[8:9], v[8:9], v[146:147], v[40:41]
	s_nop 0
	v_cvt_pk_bf16_f32 v5, v8, v9
	global_store_dword v[2:3], v5, off
	s_branch .Lrs_done
.Lrs_one:
	global_load_dword v54, v[10:11], off
	global_load_dwordx2 v[86:87], v[12:13], off
	v_lshl_add_u64 v[10:11], v[10:11], 0, s[2:3]
	global_load_dword v55, v[10:11], off
	global_load_dwordx2 v[88:89], v[12:13], off offset:1024
	v_lshl_add_u64 v[10:11], v[10:11], 0, s[2:3]
	global_load_dword v56, v[10:11], off
	global_load_dwordx2 v[90:91], v[12:13], off offset:2048
	v_lshl_add_u64 v[10:11], v[10:11], 0, s[2:3]
	global_load_dword v57, v[10:11], off
	global_load_dwordx2 v[92:93], v[12:13], off offset:3072
	v_lshl_add_u64 v[10:11], v[10:11], 0, s[2:3]
	v_lshl_add_u64 v[12:13], v[12:13], 0, vcc
	global_load_dword v58, v[10:11], off
	global_load_dwordx2 v[94:95], v[12:13], off
	v_lshl_add_u64 v[10:11], v[10:11], 0, s[2:3]
	global_load_dword v59, v[10:11], off
	global_load_dwordx2 v[96:97], v[12:13], off offset:1024
	v_lshl_add_u64 v[10:11], v[10:11], 0, s[2:3]
	global_load_dword v60, v[10:11], off
	global_load_dwordx2 v[98:99], v[12:13], off offset:2048
	v_lshl_add_u64 v[10:11], v[10:11], 0, s[2:3]
	global_load_dword v61, v[10:11], off
	global_load_dwordx2 v[100:101], v[12:13], off offset:3072
	v_cvt_pk_bf16_f32 v5, v8, v9
	global_store_dword v[2:3], v5, off
	s_waitcnt vmcnt(15)
	v_lshlrev_b32_e32 v40, 16, v54
	v_and_b32_e32 v41, 0xffff0000, v54
	v_lshl_add_u64 v[2:3], v[2:3], 0, s[2:3]
	v_pk_fma_f32 v[8:9], v[8:9], v[86:87], v[40:41]
	s_nop 0
	v_cvt_pk_bf16_f32 v5, v8, v9
	global_store_dword v[2:3], v5, off
	s_waitcnt vmcnt(14)
	v_lshlrev_b32_e32 v40, 16, v55
	v_and_b32_e32 v41, 0xffff0000, v55
	v_lshl_add_u64 v[2:3], v[2:3], 0, s[2:3]
	v_pk_fma_f32 v[8:9], v[8:9], v[88:89], v[40:41]
	s_nop 0
	v_cvt_pk_bf16_f32 v5, v8, v9
	global_store_dword v[2:3], v5, off
	s_waitcnt vmcnt(13)
	v_lshlrev_b32_e32 v40, 16, v56
	v_and_b32_e32 v41, 0xffff0000, v56
	v_lshl_add_u64 v[2:3], v[2:3], 0, s[2:3]
	v_pk_fma_f32 v[8:9], v[8:9], v[90:91], v[40:41]
	s_nop 0
	v_cvt_pk_bf16_f32 v5, v8, v9
	global_store_dword v[2:3], v5, off
	s_waitcnt vmcnt(12)
	v_lshlrev_b32_e32 v40, 16, v57
	v_and_b32_e32 v41, 0xffff0000, v57
	v_lshl_add_u64 v[2:3], v[2:3], 0, s[2:3]
	v_pk_fma_f32 v[8:9], v[8:9], v[92:93], v[40:41]
	s_nop 0
	v_cvt_pk_bf16_f32 v5, v8, v9
	global_store_dword v[2:3], v5, off
	s_waitcnt vmcnt(11)
	v_lshlrev_b32_e32 v40, 16, v58
	v_and_b32_e32 v41, 0xffff0000, v58
	v_lshl_add_u64 v[2:3], v[2:3], 0, s[2:3]
	v_pk_fma_f32 v[8:9], v[8:9], v[94:95], v[40:41]
	s_nop 0
	v_cvt_pk_bf16_f32 v5, v8, v9
	global_store_dword v[2:3], v5, off
	s_waitcnt vmcnt(10)
	v_lshlrev_b32_e32 v40, 16, v59
	v_and_b32_e32 v41, 0xffff0000, v59
	v_lshl_add_u64 v[2:3], v[2:3], 0, s[2:3]
	v_pk_fma_f32 v[8:9], v[8:9], v[96:97], v[40:41]
	s_nop 0
	v_cvt_pk_bf16_f32 v5, v8, v9
	global_store_dword v[2:3], v5, off
	s_waitcnt vmcnt(9)
	v_lshlrev_b32_e32 v40, 16, v60
	v_and_b32_e32 v41, 0xffff0000, v60
	v_lshl_add_u64 v[2:3], v[2:3], 0, s[2:3]
	v_pk_fma_f32 v[8:9], v[8:9], v[98:99], v[40:41]
	s_nop 0
	v_cvt_pk_bf16_f32 v5, v8, v9
	global_store_dword v[2:3], v5, off
.Lrs_done:
	v_add_u32_e32 v1, s0, v1
	v_cmp_le_i32_e32 vcc, s93, v1
	s_or_b64 s[6:7], vcc, s[6:7]
	s_andn2_b64 exec, exec, s[6:7]
	s_cbranch_execnz .LBB0_338
